# v20 + S5 scan: a_re / a_im loads of a unit issued together with its log_step load (one load round trip less per unit)
# baseline (speedup 1.0000x reference)
; #define GASP __attribute__((address_space(1)))
; __device__ __forceinline__ void sincos_d(double ang, float& s, float& c) { double t = ang * 0.15915494309189535; t -= rint(t); const float f = (float)t; s = __builtin_amdgcn_sinf(f); c = __builtin_amdgcn_cosf(f); }
; __global__ void __launch_bounds__(NWAVES * 64, 2) fwd_kernel(Args args) {
;     ...
;             for (int ui = 0; SO.next(ui, su); ++ui) {
;                 const int b = su.pm & 7, g = su.pm >> 3, n = lane, seg = wave, lg = l * 64 + g;
;                 const float step = expf(log_step[lg]); const float re = a_re[lg * 64 + n], im = a_im[lg * 64 + n];
;                 float aLr, aLi; { const float mag = expf(re * step * 16.f); float s, c; sincos_d((double)im * (double)step * 16.0, s, c); aLr = mag * c; aLi = mag * s; }
;                 const GASP float* Ep = (const GASP float*)(E + ((size_t)(g * 2048 + b * 256 + seg * 32)) * 128 + n);
;                 float hr[32], hi[32]; float sr = 0.f, si = 0.f;
; #pragma unroll
;                 for (int j = 0; j < 32; ++j) { const float er = Ep[(size_t)j * 128], ei = Ep[(size_t)j * 128 + 64];
;                     const float tr = aLr * sr - aLi * si + er, ti = aLr * si + aLi * sr + ei; sr = tr; si = ti; hr[j] = sr; hi[j] = si; }
.LBB0_306:
	s_ashr_i32 s25, s39, 3
	s_add_i32 s16, s25, s48
	s_ashr_i32 s17, s16, 31
	s_lshl_b64 s[18:19], s[16:17], 2
	s_add_u32 s18, s23, s18
	s_addc_u32 s19, s22, s19
	v_mov_b64_e32 v[4:5], s[18:19]
	global_load_dword v4, v[4:5], off
	v_lshl_add_u32 v6, s16, 6, v0
	v_ashrrev_i32_e32 v7, 31, v6
	v_lshlrev_b64 v[6:7], 2, v[6:7]
	v_lshl_add_u64 v[8:9], s[6:7], 0, v[6:7]
	global_load_dword v96, v[8:9], off
	v_lshl_add_u64 v[6:7], s[12:13], 0, v[6:7]
	global_load_dword v97, v[6:7], off
	s_waitcnt vmcnt(2) lgkmcnt(0)
	v_mul_f32_e32 v5, 0x3fb8aa3b, v4
	v_fma_f32 v6, v4, s91, -v5
	v_rndne_f32_e32 v7, v5
	v_fmac_f32_e32 v6, 0x32a5705f, v4
	v_sub_f32_e32 v5, v5, v7
	v_add_f32_e32 v5, v5, v6
	v_exp_f32_e32 v5, v5
	v_cvt_i32_f32_e32 v6, v7
	v_cmp_ngt_f32_e32 vcc, s40, v4
	v_ldexp_f32 v6, v5, v6
	s_nop 0
	v_cndmask_b32_e32 v6, 0, v6, vcc
	v_cmp_nlt_f32_e32 vcc, s41, v4
	v_mov_b32_e32 v5, 0
	s_nop 0
	v_cndmask_b32_e32 v10, v236, v6, vcc
	s_mov_b32 s16, 0x6dc9c883
	s_mov_b32 s17, 0x3fc45f30
	s_waitcnt vmcnt(0) lgkmcnt(0)
	v_mul_f32_e32 v4, v96, v10
	v_mul_f32_e32 v4, 0x41800000, v4
	v_mul_f32_e32 v7, 0x3fb8aa3b, v4
	v_fma_f32 v8, v4, s91, -v7
	v_rndne_f32_e32 v9, v7
	v_fmac_f32_e32 v8, 0x32a5705f, v4
	v_sub_f32_e32 v7, v7, v9
	v_add_f32_e32 v7, v7, v8
	v_exp_f32_e32 v7, v7
	v_cvt_i32_f32_e32 v8, v9
	v_cmp_ngt_f32_e32 vcc, s40, v4
	v_ldexp_f32 v7, v7, v8
	s_nop 0
	v_cndmask_b32_e32 v7, 0, v7, vcc
	v_cmp_nlt_f32_e32 vcc, s41, v4
	v_cvt_f64_f32_e32 v[8:9], v10
	s_nop 0
	v_cndmask_b32_e32 v4, v236, v7, vcc
	v_cvt_f64_f32_e32 v[6:7], v97
	v_mul_f64 v[6:7], v[8:9], v[6:7]
	v_ldexp_f64 v[6:7], v[6:7], 4
	v_mul_f64 v[8:9], v[6:7], s[16:17]
	v_rndne_f64_e32 v[8:9], v[8:9]
	v_fma_f64 v[6:7], v[6:7], s[16:17], -v[8:9]
	s_lshl_b32 s17, s39, 8
	s_and_b32 s17, s17, 0x700
	s_lshl_b32 s16, s25, 11
	s_add_i32 s17, s17, s24
	s_add_i32 s16, s17, s16
	s_ashr_i32 s17, s16, 31
	s_lshl_b64 s[18:19], s[16:17], 9
	v_lshl_add_u64 v[70:71], v[2:3], 0, s[18:19]
	global_load_dword v24, v[70:71], off
	global_load_dword v28, v[70:71], off offset:256
	global_load_dword v14, v[70:71], off offset:512
	global_load_dword v15, v[70:71], off offset:768
	global_load_dword v32, v[70:71], off offset:1024
	global_load_dword v33, v[70:71], off offset:1280
	global_load_dword v12, v[70:71], off offset:1536
	global_load_dword v13, v[70:71], off offset:1792
	global_load_dword v34, v[70:71], off offset:2048
	global_load_dword v35, v[70:71], off offset:2304
	global_load_dword v10, v[70:71], off offset:2560
	global_load_dword v11, v[70:71], off offset:2816
	global_load_dword v36, v[70:71], off offset:3072
	global_load_dword v37, v[70:71], off offset:3328
	global_load_dword v8, v[70:71], off offset:3584
	global_load_dword v9, v[70:71], off offset:3840
	s_movk_i32 s17, 0x1000
	v_add_co_u32_e32 v26, vcc, s17, v70
	s_movk_i32 s17, 0x2000
	s_nop 0
	v_addc_co_u32_e32 v27, vcc, 0, v71, vcc
	v_add_co_u32_e32 v80, vcc, s17, v70
	v_cvt_f32_f64_e32 v6, v[6:7]
	s_nop 0
	v_addc_co_u32_e32 v81, vcc, 0, v71, vcc
	global_load_dword v38, v[80:81], off offset:-4096
	global_load_dword v39, v[26:27], off offset:256
	global_load_dword v22, v[26:27], off offset:512
	global_load_dword v23, v[26:27], off offset:768
	global_load_dword v41, v[26:27], off offset:1024
	global_load_dword v43, v[26:27], off offset:1280
	global_load_dword v18, v[26:27], off offset:1536
	global_load_dword v19, v[26:27], off offset:1792
	global_load_dword v45, v[26:27], off offset:2048
	global_load_dword v49, v[26:27], off offset:2304
	global_load_dword v20, v[26:27], off offset:2560
	global_load_dword v21, v[26:27], off offset:2816
	global_load_dword v51, v[26:27], off offset:3072
	global_load_dword v55, v[26:27], off offset:3328
	global_load_dword v16, v[26:27], off offset:3584
	global_load_dword v17, v[26:27], off offset:3840
	global_load_dword v57, v[80:81], off
	global_load_dword v61, v[80:81], off offset:256
	global_load_dword v75, v[80:81], off offset:512
	global_load_dword v74, v[80:81], off offset:768
	global_load_dword v77, v[80:81], off offset:1024
	global_load_dword v76, v[80:81], off offset:1280
	global_load_dword v79, v[80:81], off offset:1536
	global_load_dword v78, v[80:81], off offset:1792
	global_load_dword v83, v[80:81], off offset:2048
	global_load_dword v82, v[80:81], off offset:2304
	global_load_dword v72, v[80:81], off offset:2560
	global_load_dword v73, v[80:81], off offset:2816
	v_sin_f32_e32 v7, v6
	v_cos_f32_e32 v6, v6
	s_movk_i32 s17, 0x3000
	v_add_co_u32_e32 v88, vcc, s17, v70
	v_pk_mul_f32 v[6:7], v[4:5], v[6:7] op_sel_hi:[0,1]
	v_pk_mul_f32 v[26:27], v[6:7], 0 op_sel_hi:[1,0]
	v_addc_co_u32_e32 v89, vcc, 0, v71, vcc
	v_add_f32_e32 v4, v26, v27
	v_pk_fma_f32 v[68:69], v[6:7], 0, v[26:27] op_sel:[0,0,1] op_sel_hi:[1,0,0] neg_lo:[0,0,1] neg_hi:[0,0,1]
	s_andn2_b64 vcc, exec, s[14:15]
	s_waitcnt vmcnt(43)
	v_add_f32_e32 v64, v68, v24
	s_waitcnt vmcnt(42)
	v_add_f32_e32 v66, v4, v28
	v_pk_mul_f32 v[26:27], v[6:7], v[66:67] op_sel:[1,0] op_sel_hi:[0,0]
	v_pk_fma_f32 v[30:31], v[6:7], v[64:65], v[26:27] neg_lo:[0,0,1] neg_hi:[0,0,1]
	v_pk_fma_f32 v[26:27], v[6:7], v[64:65], v[26:27] op_sel_hi:[1,0,1]
	s_nop 0
	v_mov_b32_e32 v31, v27
	s_waitcnt vmcnt(40)
	v_pk_add_f32 v[62:63], v[30:31], v[14:15]
	s_nop 0
	v_pk_mul_f32 v[14:15], v[6:7], v[62:63]
	s_nop 0
	v_sub_f32_e32 v4, v14, v15
	v_pk_mul_f32 v[14:15], v[6:7], v[62:63] op_sel:[0,1] op_sel_hi:[1,0]
	s_waitcnt vmcnt(39)
	v_add_f32_e32 v56, v4, v32
	v_add_f32_e32 v4, v14, v15
	s_waitcnt vmcnt(38)
	v_add_f32_e32 v60, v4, v33
	s_waitcnt vmcnt(10)
; __global__ void __launch_bounds__(NWAVES * 64, 2) fwd_kernel(Args args) {
;     ...
;                 for (int j = 0; j < 32; ++j) { const float er = Ep[(size_t)j * 128], ei = Ep[(size_t)j * 128 + 64];
;                     const float tr = aLr * sr - aLi * si + er, ti = aLr * si + aLi * sr + ei; sr = tr; si = ti; hr[j] = sr; hi[j] = si; }
	v_pk_mul_f32 v[14:15], v[6:7], v[60:61] op_sel:[1,0] op_sel_hi:[0,0]
	v_pk_fma_f32 v[26:27], v[6:7], v[56:57], v[14:15] neg_lo:[0,0,1] neg_hi:[0,0,1]
	v_pk_fma_f32 v[14:15], v[6:7], v[56:57], v[14:15] op_sel_hi:[1,0,1]
	s_nop 0
	v_mov_b32_e32 v27, v15
	v_pk_add_f32 v[58:59], v[26:27], v[12:13]
	s_nop 0
	v_pk_mul_f32 v[12:13], v[6:7], v[58:59]
	s_nop 0
	v_sub_f32_e32 v4, v12, v13
	v_pk_mul_f32 v[12:13], v[6:7], v[58:59] op_sel:[0,1] op_sel_hi:[1,0]
	v_add_f32_e32 v50, v4, v34
	v_add_f32_e32 v4, v12, v13
	v_add_f32_e32 v54, v4, v35
	v_pk_mul_f32 v[12:13], v[6:7], v[54:55] op_sel:[1,0] op_sel_hi:[0,0]
	v_pk_fma_f32 v[14:15], v[6:7], v[50:51], v[12:13] neg_lo:[0,0,1] neg_hi:[0,0,1]
	v_pk_fma_f32 v[12:13], v[6:7], v[50:51], v[12:13] op_sel_hi:[1,0,1]
	s_nop 0
	v_mov_b32_e32 v15, v13
	v_pk_add_f32 v[52:53], v[14:15], v[10:11]
	s_nop 0
	v_pk_mul_f32 v[10:11], v[6:7], v[52:53]
	s_nop 0
	v_sub_f32_e32 v4, v10, v11
	v_pk_mul_f32 v[10:11], v[6:7], v[52:53] op_sel:[0,1] op_sel_hi:[1,0]
	v_add_f32_e32 v44, v4, v36
	v_add_f32_e32 v4, v10, v11
	v_add_f32_e32 v48, v4, v37
	v_pk_mul_f32 v[10:11], v[6:7], v[48:49] op_sel:[1,0] op_sel_hi:[0,0]
	v_pk_fma_f32 v[12:13], v[6:7], v[44:45], v[10:11] neg_lo:[0,0,1] neg_hi:[0,0,1]
	v_pk_fma_f32 v[10:11], v[6:7], v[44:45], v[10:11] op_sel_hi:[1,0,1]
	s_nop 0
	v_mov_b32_e32 v13, v11
	v_pk_add_f32 v[46:47], v[12:13], v[8:9]
	s_nop 0
	v_pk_mul_f32 v[8:9], v[6:7], v[46:47]
	s_nop 0
	v_sub_f32_e32 v4, v8, v9
	v_pk_mul_f32 v[8:9], v[6:7], v[46:47] op_sel:[0,1] op_sel_hi:[1,0]
	v_add_f32_e32 v40, v4, v38
	v_add_f32_e32 v4, v8, v9
	v_add_f32_e32 v42, v4, v39
	v_pk_mul_f32 v[8:9], v[6:7], v[42:43] op_sel:[1,0] op_sel_hi:[0,0]
	v_pk_fma_f32 v[10:11], v[6:7], v[40:41], v[8:9] neg_lo:[0,0,1] neg_hi:[0,0,1]
	v_pk_fma_f32 v[8:9], v[6:7], v[40:41], v[8:9] op_sel_hi:[1,0,1]
	s_nop 0
	v_mov_b32_e32 v11, v9
	v_pk_add_f32 v[38:39], v[10:11], v[22:23]
	s_nop 0
	v_pk_mul_f32 v[8:9], v[6:7], v[38:39]
	s_nop 0
	v_sub_f32_e32 v4, v8, v9
	v_pk_mul_f32 v[8:9], v[6:7], v[38:39] op_sel:[0,1] op_sel_hi:[1,0]
	v_add_f32_e32 v34, v4, v41
	v_add_f32_e32 v4, v8, v9
	v_add_f32_e32 v36, v4, v43
	v_pk_mul_f32 v[8:9], v[6:7], v[36:37] op_sel:[1,0] op_sel_hi:[0,0]
	v_pk_fma_f32 v[10:11], v[6:7], v[34:35], v[8:9] neg_lo:[0,0,1] neg_hi:[0,0,1]
	v_pk_fma_f32 v[8:9], v[6:7], v[34:35], v[8:9] op_sel_hi:[1,0,1]
	s_nop 0
	v_mov_b32_e32 v11, v9
	v_pk_add_f32 v[32:33], v[10:11], v[18:19]
	s_nop 0
	v_pk_mul_f32 v[8:9], v[6:7], v[32:33]
	s_nop 0
	v_sub_f32_e32 v4, v8, v9
	v_pk_mul_f32 v[8:9], v[6:7], v[32:33] op_sel:[0,1] op_sel_hi:[1,0]
	v_add_f32_e32 v28, v4, v45
	v_add_f32_e32 v4, v8, v9
	v_add_f32_e32 v30, v4, v49
	v_pk_mul_f32 v[8:9], v[6:7], v[30:31] op_sel:[1,0] op_sel_hi:[0,0]
	v_pk_fma_f32 v[10:11], v[6:7], v[28:29], v[8:9] neg_lo:[0,0,1] neg_hi:[0,0,1]
	v_pk_fma_f32 v[8:9], v[6:7], v[28:29], v[8:9] op_sel_hi:[1,0,1]
	s_nop 0
	v_mov_b32_e32 v11, v9
	v_pk_add_f32 v[26:27], v[10:11], v[20:21]
	s_nop 0
	v_pk_mul_f32 v[8:9], v[6:7], v[26:27]
	s_nop 0
	v_sub_f32_e32 v4, v8, v9
	v_pk_mul_f32 v[8:9], v[6:7], v[26:27] op_sel:[0,1] op_sel_hi:[1,0]
	v_add_f32_e32 v22, v4, v51
	v_add_f32_e32 v4, v8, v9
	v_add_f32_e32 v24, v4, v55
	v_pk_mul_f32 v[8:9], v[6:7], v[24:25] op_sel:[1,0] op_sel_hi:[0,0]
	v_pk_fma_f32 v[10:11], v[6:7], v[22:23], v[8:9] neg_lo:[0,0,1] neg_hi:[0,0,1]
	v_pk_fma_f32 v[8:9], v[6:7], v[22:23], v[8:9] op_sel_hi:[1,0,1]
	s_nop 0
	v_mov_b32_e32 v11, v9
	v_pk_add_f32 v[20:21], v[10:11], v[16:17]
	s_nop 0
	v_pk_mul_f32 v[8:9], v[6:7], v[20:21]
	s_nop 0
	v_sub_f32_e32 v4, v8, v9
	v_pk_mul_f32 v[8:9], v[6:7], v[20:21] op_sel:[0,1] op_sel_hi:[1,0]
	v_add_f32_e32 v16, v4, v57
	v_add_f32_e32 v4, v8, v9
	v_add_f32_e32 v18, v4, v61
	v_pk_mul_f32 v[8:9], v[6:7], v[18:19] op_sel_hi:[1,0]
	s_nop 0
	v_pk_fma_f32 v[10:11], v[6:7], v[16:17], v[8:9] op_sel:[1,0,0] op_sel_hi:[0,1,1]
	v_pk_fma_f32 v[8:9], v[6:7], v[16:17], v[8:9] op_sel:[1,0,0] op_sel_hi:[0,0,1] neg_lo:[0,0,1] neg_hi:[0,0,1]
	v_mov_b32_e32 v11, v9
	s_waitcnt vmcnt(8)
	v_pk_add_f32 v[14:15], v[10:11], v[74:75]
	s_nop 0
	v_pk_mul_f32 v[8:9], v[6:7], v[14:15] op_sel:[1,0]
	s_nop 0
	v_pk_fma_f32 v[10:11], v[6:7], v[14:15], v[8:9] op_sel:[0,0,1] op_sel_hi:[1,1,0]
	v_pk_fma_f32 v[8:9], v[6:7], v[14:15], v[8:9] op_sel:[0,0,1] op_sel_hi:[0,1,0] neg_lo:[0,0,1] neg_hi:[0,0,1]
	v_mov_b32_e32 v11, v9
	s_waitcnt vmcnt(6)
	v_pk_add_f32 v[12:13], v[10:11], v[76:77]
	s_nop 0
	v_pk_mul_f32 v[8:9], v[6:7], v[12:13] op_sel:[1,0]
	s_nop 0
	v_pk_fma_f32 v[10:11], v[6:7], v[12:13], v[8:9] op_sel:[0,0,1] op_sel_hi:[1,1,0]
	v_pk_fma_f32 v[8:9], v[6:7], v[12:13], v[8:9] op_sel:[0,0,1] op_sel_hi:[0,1,0] neg_lo:[0,0,1] neg_hi:[0,0,1]
	v_mov_b32_e32 v11, v9
	s_waitcnt vmcnt(4)
	v_pk_add_f32 v[10:11], v[10:11], v[78:79]
	s_nop 0
	v_pk_mul_f32 v[8:9], v[6:7], v[10:11] op_sel:[1,0]
	s_nop 0
	v_pk_fma_f32 v[74:75], v[6:7], v[10:11], v[8:9] op_sel:[0,0,1] op_sel_hi:[1,1,0]
	v_pk_fma_f32 v[8:9], v[6:7], v[10:11], v[8:9] op_sel:[0,0,1] op_sel_hi:[0,1,0] neg_lo:[0,0,1] neg_hi:[0,0,1]
	v_mov_b32_e32 v75, v9
	s_waitcnt vmcnt(2)
	v_pk_add_f32 v[8:9], v[74:75], v[82:83]
	global_load_dword v74, v[80:81], off offset:3072
	global_load_dword v75, v[80:81], off offset:3328
	global_load_dword v78, v[80:81], off offset:3584
	global_load_dword v79, v[80:81], off offset:3840
	global_load_dword v70, v[88:89], off
	global_load_dword v71, v[88:89], off offset:256
	v_mul_f32_e32 v4, v7, v8
	v_pk_fma_f32 v[76:77], v[6:7], v[8:9], v[4:5] op_sel:[0,1,0] op_sel_hi:[1,0,0] neg_lo:[0,0,1] neg_hi:[0,0,1]
	v_mul_f32_e32 v4, v6, v8
	v_pk_fma_f32 v[82:83], v[6:7], v[8:9], v[4:5] op_sel_hi:[1,1,0]
	v_mov_b32_e32 v4, v5
	v_mov_b32_e32 v77, v83
	s_waitcnt vmcnt(6)
; __global__ void __launch_bounds__(NWAVES * 64, 2) fwd_kernel(Args args) {
;     ...
;                 for (int j = 0; j < 32; ++j) { const float er = Ep[(size_t)j * 128], ei = Ep[(size_t)j * 128 + 64];
;                     const float tr = aLr * sr - aLi * si + er, ti = aLr * si + aLi * sr + ei; sr = tr; si = ti; hr[j] = sr; hi[j] = si; }
;                 tot[(seg * 64 + n) * 2] = sr; tot[(seg * 64 + n) * 2 + 1] = si;
;                 float pr = aLr, pi = aLi;
; #pragma unroll
;                 for (int q = 0; q < 5; ++q) { const float tr = pr * pr - pi * pi, ti = 2.f * pr * pi; pr = tr; pi = ti; }
;                 __syncthreads();
;                 float cr = 0.f, ci = 0.f;
;                 for (int s2 = 0; s2 < seg; ++s2) { const float tr = pr * cr - pi * ci + tot[(s2 * 64 + n) * 2], ti = pr * ci + pi * cr + tot[(s2 * 64 + n) * 2 + 1]; cr = tr; ci = ti; }
	v_pk_add_f32 v[76:77], v[76:77], v[72:73]
	s_nop 0
	v_pk_mul_f32 v[72:73], v[6:7], v[76:77] op_sel:[1,0]
	s_nop 0
	v_pk_fma_f32 v[80:81], v[6:7], v[76:77], v[72:73] op_sel:[0,0,1] op_sel_hi:[1,1,0] neg_lo:[0,0,1] neg_hi:[0,0,1]
	v_pk_fma_f32 v[72:73], v[6:7], v[76:77], v[72:73] op_sel:[0,0,1] op_sel_hi:[0,1,0]
	v_mov_b32_e32 v81, v73
	s_waitcnt vmcnt(4)
	v_pk_add_f32 v[74:75], v[80:81], v[74:75]
	s_nop 0
	v_pk_mul_f32 v[72:73], v[6:7], v[74:75] op_sel:[1,0]
	s_nop 0
	v_pk_fma_f32 v[80:81], v[6:7], v[74:75], v[72:73] op_sel:[0,0,1] op_sel_hi:[1,1,0] neg_lo:[0,0,1] neg_hi:[0,0,1]
	v_pk_fma_f32 v[72:73], v[6:7], v[74:75], v[72:73] op_sel:[0,0,1] op_sel_hi:[0,1,0]
	v_mov_b32_e32 v81, v73
	s_waitcnt vmcnt(2)
	v_pk_add_f32 v[72:73], v[80:81], v[78:79]
	s_nop 0
	v_pk_mul_f32 v[78:79], v[6:7], v[72:73] op_sel:[1,0]
	s_nop 0
	v_pk_fma_f32 v[80:81], v[6:7], v[72:73], v[78:79] op_sel:[0,0,1] op_sel_hi:[1,1,0] neg_lo:[0,0,1] neg_hi:[0,0,1]
	v_pk_fma_f32 v[78:79], v[6:7], v[72:73], v[78:79] op_sel:[0,0,1] op_sel_hi:[0,1,0]
	v_mov_b32_e32 v81, v79
	s_waitcnt vmcnt(0)
	v_pk_add_f32 v[70:71], v[80:81], v[70:71]
	global_load_dword v78, v[88:89], off offset:512
	global_load_dword v79, v[88:89], off offset:768
	global_load_dword v80, v[88:89], off offset:1024
	global_load_dword v81, v[88:89], off offset:1280
	global_load_dword v86, v[88:89], off offset:1536
	global_load_dword v87, v[88:89], off offset:1792
	global_load_dword v84, v[88:89], off offset:2048
	global_load_dword v85, v[88:89], off offset:2304
	v_pk_mul_f32 v[82:83], v[6:7], v[70:71] op_sel:[1,0]
	s_nop 0
	v_pk_fma_f32 v[90:91], v[6:7], v[70:71], v[82:83] op_sel:[0,0,1] op_sel_hi:[1,1,0] neg_lo:[0,0,1] neg_hi:[0,0,1]
	v_pk_fma_f32 v[82:83], v[6:7], v[70:71], v[82:83] op_sel:[0,0,1] op_sel_hi:[0,1,0]
	v_mov_b32_e32 v91, v83
	s_waitcnt vmcnt(6)
	v_pk_add_f32 v[82:83], v[90:91], v[78:79]
	s_nop 0
	v_pk_mul_f32 v[78:79], v[6:7], v[82:83] op_sel:[1,0]
	s_nop 0
	v_pk_fma_f32 v[90:91], v[6:7], v[82:83], v[78:79] op_sel:[0,0,1] op_sel_hi:[1,1,0] neg_lo:[0,0,1] neg_hi:[0,0,1]
	v_pk_fma_f32 v[78:79], v[6:7], v[82:83], v[78:79] op_sel:[0,0,1] op_sel_hi:[0,1,0]
	v_mov_b32_e32 v91, v79
	s_waitcnt vmcnt(4)
	v_pk_add_f32 v[80:81], v[90:91], v[80:81]
	s_nop 0
	v_pk_mul_f32 v[78:79], v[6:7], v[80:81] op_sel:[1,0]
	s_nop 0
	v_pk_fma_f32 v[90:91], v[6:7], v[80:81], v[78:79] op_sel:[0,0,1] op_sel_hi:[1,1,0] neg_lo:[0,0,1] neg_hi:[0,0,1]
	v_pk_fma_f32 v[78:79], v[6:7], v[80:81], v[78:79] op_sel:[0,0,1] op_sel_hi:[0,1,0]
	v_mov_b32_e32 v91, v79
	s_waitcnt vmcnt(2)
	v_pk_add_f32 v[78:79], v[90:91], v[86:87]
	s_nop 0
	v_pk_mul_f32 v[90:91], v[6:7], v[78:79] op_sel:[1,0]
	s_nop 0
	v_pk_fma_f32 v[86:87], v[6:7], v[78:79], v[90:91] op_sel:[0,0,1] op_sel_hi:[1,1,0] neg_lo:[0,0,1] neg_hi:[0,0,1]
	v_pk_fma_f32 v[90:91], v[6:7], v[78:79], v[90:91] op_sel:[0,0,1] op_sel_hi:[0,1,0]
	v_mov_b32_e32 v87, v91
	global_load_dword v94, v[88:89], off offset:2560
	global_load_dword v95, v[88:89], off offset:2816
	global_load_dword v92, v[88:89], off offset:3072
	global_load_dword v93, v[88:89], off offset:3328
	global_load_dword v90, v[88:89], off offset:3584
	global_load_dword v91, v[88:89], off offset:3840
	s_waitcnt vmcnt(6)
	v_pk_add_f32 v[88:89], v[86:87], v[84:85]
	s_nop 0
	v_pk_mul_f32 v[84:85], v[6:7], v[88:89] op_sel:[1,0]
	s_nop 0
	v_pk_fma_f32 v[86:87], v[6:7], v[88:89], v[84:85] op_sel:[0,0,1] op_sel_hi:[1,1,0] neg_lo:[0,0,1] neg_hi:[0,0,1]
	v_pk_fma_f32 v[84:85], v[6:7], v[88:89], v[84:85] op_sel:[0,0,1] op_sel_hi:[0,1,0]
	v_mov_b32_e32 v87, v85
	s_waitcnt vmcnt(4)
	v_pk_add_f32 v[86:87], v[86:87], v[94:95]
	s_nop 0
	v_pk_mul_f32 v[84:85], v[6:7], v[86:87] op_sel:[1,0]
	s_nop 0
	v_pk_fma_f32 v[94:95], v[6:7], v[86:87], v[84:85] op_sel:[0,0,1] op_sel_hi:[1,1,0] neg_lo:[0,0,1] neg_hi:[0,0,1]
	v_pk_fma_f32 v[84:85], v[6:7], v[86:87], v[84:85] op_sel:[0,0,1] op_sel_hi:[0,1,0]
	v_mov_b32_e32 v95, v85
	s_waitcnt vmcnt(2)
	v_pk_add_f32 v[84:85], v[94:95], v[92:93]
	s_nop 0
	v_pk_mul_f32 v[92:93], v[6:7], v[84:85] op_sel:[1,0]
	s_nop 0
	v_pk_fma_f32 v[94:95], v[6:7], v[84:85], v[92:93] op_sel:[0,0,1] op_sel_hi:[1,1,0] neg_lo:[0,0,1] neg_hi:[0,0,1]
	v_pk_fma_f32 v[92:93], v[6:7], v[84:85], v[92:93] op_sel:[0,0,1] op_sel_hi:[0,1,0]
	v_mov_b32_e32 v95, v93
	s_waitcnt vmcnt(0)
	v_pk_add_f32 v[90:91], v[94:95], v[90:91]
	ds_write_b64 v29, v[90:91]
	s_waitcnt lgkmcnt(0)
	s_barrier
	s_cbranch_vccnz .LBB0_297
	v_pk_mul_f32 v[4:5], v[6:7], v[6:7]
	s_mov_b32 s17, s20
	v_sub_f32_e32 v4, v4, v5
	v_add_f32_e32 v5, v6, v6
	v_mul_f32_e32 v5, v7, v5
	v_mul_f32_e32 v17, v4, v4
	v_add_f32_e32 v4, v4, v4
	v_mul_f32_e32 v4, v5, v4
	v_fma_f32 v17, -v5, v5, v17
	v_mul_f32_e32 v5, v4, v4
	v_fma_f32 v5, v17, v17, -v5
	v_add_f32_e32 v17, v17, v17
	v_mul_f32_e32 v4, v4, v17
	v_mul_f32_e32 v17, v4, v4
	v_fma_f32 v17, v5, v5, -v17
	v_add_f32_e32 v5, v5, v5
	v_mul_f32_e32 v4, v4, v5
	v_mul_f32_e32 v5, v4, v4
	v_fma_f32 v68, v17, v17, -v5
	v_add_f32_e32 v5, v17, v17
	v_mul_f32_e32 v90, v4, v5
	v_mov_b32_e32 v4, 0
	v_mov_b32_e32 v69, v68
	v_mov_b32_e32 v91, v90
	v_mov_b32_e32 v17, v25
	v_mov_b32_e32 v5, v4
